# v56 + nt (streaming) hint on the attention phase's O stores
# speedup vs baseline: 1.0088x; 1.0088x over previous
; __device__ __forceinline__ unsigned cvtpk(float lo, float hi) { f32x2 v = {lo, hi}; bf16x2_t b = __builtin_convertvector(v, bf16x2_t); return __builtin_bit_cast(unsigned, b); }
; template <int MODE, bool FIX> ...
;     ...
;     bf16_t* op = O + orow * DM + ocol + (hi ? 8 : 0);
; #pragma unroll
;     for (int j = 0; j < 2; ++j) {
;         u32x2 a0, b0, a1, b1;
;         a0.x = cvtpk(o0[8 * j], o0[8 * j + 1]); a0.y = cvtpk(o0[8 * j + 2], o0[8 * j + 3]); b0.x = cvtpk(o0[8 * j + 4], o0[8 * j + 5]); b0.y = cvtpk(o0[8 * j + 6], o0[8 * j + 7]);
;         a1.x = cvtpk(o1[8 * j], o1[8 * j + 1]); a1.y = cvtpk(o1[8 * j + 2], o1[8 * j + 3]); b1.x = cvtpk(o1[8 * j + 4], o1[8 * j + 5]); b1.y = cvtpk(o1[8 * j + 6], o1[8 * j + 7]);
;         auto x0 = __builtin_amdgcn_permlane32_swap(a0.x, b0.x, false, false); auto y0 = __builtin_amdgcn_permlane32_swap(a0.y, b0.y, false, false);
;         auto x1 = __builtin_amdgcn_permlane32_swap(a1.x, b1.x, false, false); auto y1 = __builtin_amdgcn_permlane32_swap(a1.y, b1.y, false, false);
;         u32x4 w0, w1; w0.x = x0[0]; w0.y = y0[0]; w0.z = x0[1]; w0.w = y0[1]; w1.x = x1[0]; w1.y = y1[0]; w1.z = x1[1]; w1.w = y1[1];
;         *(u32x4*)(op + 16 * j) = w0; *(u32x4*)(op + 32 + 16 * j) = w1;
;     }
;     asm volatile("s_waitcnt lgkmcnt(0)\n\ts_barrier" ::: "memory");
.LBB0_571:
	s_or_b64 exec, exec, s[70:71]
	v_lshlrev_b64 v[52:53], 11, v[128:129]
	v_lshl_add_u64 v[52:53], s[78:79], 0, v[52:53]
	v_lshl_add_u64 v[52:53], v[52:53], 0, s[86:87]
	v_lshlrev_b32_e32 v0, 1, v50
	v_lshl_add_u64 v[54:55], v[52:53], 0, v[0:1]
	v_cvt_pk_bf16_f32 v50, v4, v5
	v_cvt_pk_bf16_f32 v51, v8, v9
	v_cvt_pk_bf16_f32 v52, v32, v33
	v_cvt_pk_bf16_f32 v53, v48, v49
	v_cvt_pk_bf16_f32 v2, v2, v3
	v_cvt_pk_bf16_f32 v3, v6, v7
	v_cvt_pk_bf16_f32 v4, v14, v15
	v_cvt_pk_bf16_f32 v5, v38, v39
	v_permlane32_swap_b32_e32 v50, v52
	v_permlane32_swap_b32_e32 v51, v53
	v_permlane32_swap_b32_e32 v2, v4
	v_permlane32_swap_b32_e32 v3, v5
	global_store_dwordx4 v[54:55], v[50:53], off nt
	global_store_dwordx4 v[54:55], v[2:5], off offset:64 nt
	v_cvt_pk_bf16_f32 v6, v10, v11
	v_cvt_pk_bf16_f32 v7, v34, v35
	v_cvt_pk_bf16_f32 v2, v12, v13
	v_cvt_pk_bf16_f32 v3, v36, v37
	v_cvt_pk_bf16_f32 v4, v42, v43
	v_cvt_pk_bf16_f32 v5, v46, v47
	v_cvt_pk_bf16_f32 v8, v40, v41
	v_cvt_pk_bf16_f32 v9, v44, v45
	v_permlane32_swap_b32_e32 v2, v4
	v_permlane32_swap_b32_e32 v3, v5
	v_permlane32_swap_b32_e32 v6, v8
	v_permlane32_swap_b32_e32 v7, v9
	global_store_dwordx4 v[54:55], v[2:5], off offset:32 nt
	global_store_dwordx4 v[54:55], v[6:9], off offset:96 nt
	s_waitcnt lgkmcnt(0)
	s_barrier

; __device__ __forceinline__ unsigned cvtpk(float lo, float hi) { f32x2 v = {lo, hi}; bf16x2_t b = __builtin_convertvector(v, bf16x2_t); return __builtin_bit_cast(unsigned, b); }
; template <int MODE, bool FIX> ...
;     ...
;     bf16_t* op = O + orow * DM + ocol + (hi ? 8 : 0);
; #pragma unroll
;     for (int j = 0; j < 2; ++j) {
;         u32x2 a0, b0, a1, b1;
;         a0.x = cvtpk(o0[8 * j], o0[8 * j + 1]); a0.y = cvtpk(o0[8 * j + 2], o0[8 * j + 3]); b0.x = cvtpk(o0[8 * j + 4], o0[8 * j + 5]); b0.y = cvtpk(o0[8 * j + 6], o0[8 * j + 7]);
;         a1.x = cvtpk(o1[8 * j], o1[8 * j + 1]); a1.y = cvtpk(o1[8 * j + 2], o1[8 * j + 3]); b1.x = cvtpk(o1[8 * j + 4], o1[8 * j + 5]); b1.y = cvtpk(o1[8 * j + 6], o1[8 * j + 7]);
;         auto x0 = __builtin_amdgcn_permlane32_swap(a0.x, b0.x, false, false); auto y0 = __builtin_amdgcn_permlane32_swap(a0.y, b0.y, false, false);
;         auto x1 = __builtin_amdgcn_permlane32_swap(a1.x, b1.x, false, false); auto y1 = __builtin_amdgcn_permlane32_swap(a1.y, b1.y, false, false);
;         u32x4 w0, w1; w0.x = x0[0]; w0.y = y0[0]; w0.z = x0[1]; w0.w = y0[1]; w1.x = x1[0]; w1.y = y1[0]; w1.z = x1[1]; w1.w = y1[1];
;         *(u32x4*)(op + 16 * j) = w0; *(u32x4*)(op + 32 + 16 * j) = w1;
;     }
;     asm volatile("s_waitcnt lgkmcnt(0)\n\ts_barrier" ::: "memory");
.LBB0_654:
	s_or_b64 exec, exec, s[70:71]
	v_readlane_b32 s78, v255, 29
	v_lshlrev_b64 v[52:53], 11, v[184:185]
	v_readlane_b32 s79, v255, 30
	v_lshlrev_b32_e32 v0, 1, v46
	v_cvt_pk_bf16_f32 v54, v32, v33
	v_lshl_add_u64 v[52:53], s[78:79], 0, v[52:53]
	v_lshl_add_u64 v[52:53], v[52:53], 0, s[86:87]
	v_lshl_add_u64 v[46:47], v[52:53], 0, v[0:1]
	v_cvt_pk_bf16_f32 v52, v4, v5
	v_cvt_pk_bf16_f32 v53, v8, v9
	v_cvt_pk_bf16_f32 v55, v48, v49
	v_cvt_pk_bf16_f32 v2, v2, v3
	v_cvt_pk_bf16_f32 v3, v6, v7
	v_cvt_pk_bf16_f32 v4, v14, v15
	v_cvt_pk_bf16_f32 v5, v38, v39
	v_permlane32_swap_b32_e32 v52, v54
	v_permlane32_swap_b32_e32 v53, v55
	v_permlane32_swap_b32_e32 v2, v4
	v_permlane32_swap_b32_e32 v3, v5
	global_store_dwordx4 v[46:47], v[52:55], off nt
	global_store_dwordx4 v[46:47], v[2:5], off offset:64 nt
	v_cvt_pk_bf16_f32 v6, v10, v11
	v_cvt_pk_bf16_f32 v7, v34, v35
	v_cvt_pk_bf16_f32 v2, v12, v13
	v_cvt_pk_bf16_f32 v3, v36, v37
	v_cvt_pk_bf16_f32 v4, v42, v43
	v_cvt_pk_bf16_f32 v5, v50, v51
	v_cvt_pk_bf16_f32 v8, v40, v41
	v_cvt_pk_bf16_f32 v9, v44, v45
	v_permlane32_swap_b32_e32 v2, v4
	v_permlane32_swap_b32_e32 v3, v5
	v_permlane32_swap_b32_e32 v6, v8
	v_permlane32_swap_b32_e32 v7, v9
	global_store_dwordx4 v[46:47], v[2:5], off offset:32 nt
	global_store_dwordx4 v[46:47], v[6:9], off offset:96 nt
	s_waitcnt lgkmcnt(0)
	s_barrier
	s_mov_b64 s[70:71], 0
	v_readlane_b32 s85, v255, 31
	v_readlane_b32 s80, v255, 32
	v_readlane_b32 s81, v255, 33

; __device__ __forceinline__ unsigned cvtpk(float lo, float hi) { f32x2 v = {lo, hi}; bf16x2_t b = __builtin_convertvector(v, bf16x2_t); return __builtin_bit_cast(unsigned, b); }
; template <int MODE, bool FIX> ...
;     ...
;     bf16_t* op = O + orow * DM + ocol + (hi ? 8 : 0);
; #pragma unroll
;     for (int j = 0; j < 2; ++j) {
;         u32x2 a0, b0, a1, b1;
;         a0.x = cvtpk(o0[8 * j], o0[8 * j + 1]); a0.y = cvtpk(o0[8 * j + 2], o0[8 * j + 3]); b0.x = cvtpk(o0[8 * j + 4], o0[8 * j + 5]); b0.y = cvtpk(o0[8 * j + 6], o0[8 * j + 7]);
;         a1.x = cvtpk(o1[8 * j], o1[8 * j + 1]); a1.y = cvtpk(o1[8 * j + 2], o1[8 * j + 3]); b1.x = cvtpk(o1[8 * j + 4], o1[8 * j + 5]); b1.y = cvtpk(o1[8 * j + 6], o1[8 * j + 7]);
;         auto x0 = __builtin_amdgcn_permlane32_swap(a0.x, b0.x, false, false); auto y0 = __builtin_amdgcn_permlane32_swap(a0.y, b0.y, false, false);
;         auto x1 = __builtin_amdgcn_permlane32_swap(a1.x, b1.x, false, false); auto y1 = __builtin_amdgcn_permlane32_swap(a1.y, b1.y, false, false);
;         u32x4 w0, w1; w0.x = x0[0]; w0.y = y0[0]; w0.z = x0[1]; w0.w = y0[1]; w1.x = x1[0]; w1.y = y1[0]; w1.z = x1[1]; w1.w = y1[1];
;         *(u32x4*)(op + 16 * j) = w0; *(u32x4*)(op + 32 + 16 * j) = w1;
;     }
;     asm volatile("s_waitcnt lgkmcnt(0)\n\ts_barrier" ::: "memory");
.LBB0_675:
	s_or_b64 exec, exec, s[8:9]
	v_lshlrev_b64 v[14:15], 11, v[14:15]
	v_lshl_add_u64 v[14:15], s[78:79], 0, v[14:15]
	s_lshl_b32 s42, s10, 1
	v_lshl_add_u64 v[14:15], v[14:15], 0, s[42:43]
	v_lshlrev_b32_e32 v0, 1, v52
	v_cvt_pk_bf16_f32 v52, v4, v5
	v_cvt_pk_bf16_f32 v53, v8, v9
	v_cvt_pk_bf16_f32 v54, v34, v35
	v_cvt_pk_bf16_f32 v55, v50, v51
	v_cvt_pk_bf16_f32 v2, v2, v3
	v_cvt_pk_bf16_f32 v3, v6, v7
	v_cvt_pk_bf16_f32 v4, v32, v33
	v_cvt_pk_bf16_f32 v5, v48, v49
	v_lshl_add_u64 v[14:15], v[14:15], 0, v[0:1]
	v_permlane32_swap_b32_e32 v52, v54
	v_permlane32_swap_b32_e32 v53, v55
	v_permlane32_swap_b32_e32 v2, v4
	v_permlane32_swap_b32_e32 v3, v5
	global_store_dwordx4 v[14:15], v[52:55], off offset:1024 nt
	global_store_dwordx4 v[14:15], v[2:5], off offset:1088 nt
	v_cvt_pk_bf16_f32 v6, v10, v11
	v_cvt_pk_bf16_f32 v7, v36, v37
	v_cvt_pk_bf16_f32 v2, v12, v13
	v_cvt_pk_bf16_f32 v3, v38, v39
	v_cvt_pk_bf16_f32 v4, v42, v43
	v_cvt_pk_bf16_f32 v5, v46, v47
	v_cvt_pk_bf16_f32 v8, v40, v41
	v_cvt_pk_bf16_f32 v9, v44, v45
	v_permlane32_swap_b32_e32 v2, v4
	v_permlane32_swap_b32_e32 v3, v5
	v_permlane32_swap_b32_e32 v6, v8
	v_permlane32_swap_b32_e32 v7, v9
	global_store_dwordx4 v[14:15], v[2:5], off offset:1056 nt
	global_store_dwordx4 v[14:15], v[6:9], off offset:1120 nt
	s_waitcnt lgkmcnt(0)
	s_barrier

; __device__ __forceinline__ unsigned cvtpk(float lo, float hi) { f32x2 v = {lo, hi}; bf16x2_t b = __builtin_convertvector(v, bf16x2_t); return __builtin_bit_cast(unsigned, b); }
; template <int MODE, bool FIX> ...
;     ...
;     bf16_t* op = O + orow * DM + ocol + (hi ? 8 : 0);
; #pragma unroll
;     for (int j = 0; j < 2; ++j) {
;         u32x2 a0, b0, a1, b1;
;         a0.x = cvtpk(o0[8 * j], o0[8 * j + 1]); a0.y = cvtpk(o0[8 * j + 2], o0[8 * j + 3]); b0.x = cvtpk(o0[8 * j + 4], o0[8 * j + 5]); b0.y = cvtpk(o0[8 * j + 6], o0[8 * j + 7]);
;         a1.x = cvtpk(o1[8 * j], o1[8 * j + 1]); a1.y = cvtpk(o1[8 * j + 2], o1[8 * j + 3]); b1.x = cvtpk(o1[8 * j + 4], o1[8 * j + 5]); b1.y = cvtpk(o1[8 * j + 6], o1[8 * j + 7]);
;         auto x0 = __builtin_amdgcn_permlane32_swap(a0.x, b0.x, false, false); auto y0 = __builtin_amdgcn_permlane32_swap(a0.y, b0.y, false, false);
;         auto x1 = __builtin_amdgcn_permlane32_swap(a1.x, b1.x, false, false); auto y1 = __builtin_amdgcn_permlane32_swap(a1.y, b1.y, false, false);
;         u32x4 w0, w1; w0.x = x0[0]; w0.y = y0[0]; w0.z = x0[1]; w0.w = y0[1]; w1.x = x1[0]; w1.y = y1[0]; w1.z = x1[1]; w1.w = y1[1];
;         *(u32x4*)(op + 16 * j) = w0; *(u32x4*)(op + 32 + 16 * j) = w1;
;     }
;     asm volatile("s_waitcnt lgkmcnt(0)\n\ts_barrier" ::: "memory");
.LBB0_721:
	s_or_b64 exec, exec, s[8:9]
	v_lshlrev_b64 v[52:53], 11, v[144:145]
	v_lshl_add_u64 v[52:53], s[78:79], 0, v[52:53]
	s_lshl_b32 s42, s17, 1
	v_lshl_add_u64 v[52:53], v[52:53], 0, s[42:43]
	v_lshlrev_b32_e32 v0, 1, v50
	v_lshl_add_u64 v[54:55], v[52:53], 0, v[0:1]
	v_cvt_pk_bf16_f32 v50, v4, v5
	v_cvt_pk_bf16_f32 v51, v8, v9
	v_cvt_pk_bf16_f32 v52, v32, v33
	v_cvt_pk_bf16_f32 v53, v48, v49
	v_cvt_pk_bf16_f32 v2, v2, v3
	v_cvt_pk_bf16_f32 v3, v6, v7
	v_cvt_pk_bf16_f32 v4, v14, v15
	v_cvt_pk_bf16_f32 v5, v38, v39
	v_permlane32_swap_b32_e32 v50, v52
	v_permlane32_swap_b32_e32 v51, v53
	v_permlane32_swap_b32_e32 v2, v4
	v_permlane32_swap_b32_e32 v3, v5
	global_store_dwordx4 v[54:55], v[50:53], off offset:1024 nt
	global_store_dwordx4 v[54:55], v[2:5], off offset:1088 nt
	v_cvt_pk_bf16_f32 v6, v10, v11
	v_cvt_pk_bf16_f32 v7, v34, v35
	v_cvt_pk_bf16_f32 v2, v12, v13
	v_cvt_pk_bf16_f32 v3, v36, v37
	v_cvt_pk_bf16_f32 v4, v42, v43
	v_cvt_pk_bf16_f32 v5, v46, v47
	v_cvt_pk_bf16_f32 v8, v40, v41
	v_cvt_pk_bf16_f32 v9, v44, v45
	v_permlane32_swap_b32_e32 v2, v4
	v_permlane32_swap_b32_e32 v3, v5
	v_permlane32_swap_b32_e32 v6, v8
	v_permlane32_swap_b32_e32 v7, v9
	global_store_dwordx4 v[54:55], v[2:5], off offset:1056 nt
	global_store_dwordx4 v[54:55], v[6:9], off offset:1120 nt
	s_waitcnt lgkmcnt(0)
	s_barrier
	s_mov_b64 s[8:9], 0
